# stack: v34 plus pipelined prep u/v conversion loop, all 64 adaLN weight loads of a job issued together, and the attention VALU trim
# baseline (speedup 1.0000x reference)
; __device__ void phase_prep(const Params& p, int bid, int nb, char* lds) {
;     ...
;       const int cl = tid & 15, dq = tid >> 4, col = j * 16 + cl;
;       float a0 = 0, a1 = 0, a2 = 0, a3 = 0;
;       const float* wp = p.w_ada + (size_t)(dq * 64) * 6144 + col;
; #pragma unroll 8
;       for (int d = 0; d < 64; ++d) {
;         float wv = wp[(size_t)d * 6144];
;         const int dd = dq * 64 + d;
;         a0 += wv * sc[dd]; a1 += wv * sc[1024 + dd]; a2 += wv * sc[2048 + dd]; a3 += wv * sc[3072 + dd];
.LBB0_56:
	global_load_dword v184, v[0:1], off
	v_add_co_u32_e32 v42, vcc, 0x6000, v0
	s_nop 1
	v_addc_co_u32_e32 v43, vcc, 0, v1, vcc
	global_load_dword v185, v[42:43], off
	v_add_co_u32_e32 v40, vcc, 0xc000, v0
	s_nop 1
	v_addc_co_u32_e32 v41, vcc, 0, v1, vcc
	global_load_dword v186, v[40:41], off
	v_add_co_u32_e32 v42, vcc, 0x12000, v0
	s_nop 1
	v_addc_co_u32_e32 v43, vcc, 0, v1, vcc
	global_load_dword v187, v[42:43], off
	v_add_co_u32_e32 v40, vcc, 0x18000, v0
	s_nop 1
	v_addc_co_u32_e32 v41, vcc, 0, v1, vcc
	global_load_dword v188, v[40:41], off
	v_add_co_u32_e32 v42, vcc, 0x1e000, v0
	s_nop 1
	v_addc_co_u32_e32 v43, vcc, 0, v1, vcc
	global_load_dword v189, v[42:43], off
	v_add_co_u32_e32 v40, vcc, 0x24000, v0
	s_nop 1
	v_addc_co_u32_e32 v41, vcc, 0, v1, vcc
	global_load_dword v190, v[40:41], off
	v_add_co_u32_e32 v42, vcc, 0x2a000, v0
	s_nop 1
	v_addc_co_u32_e32 v43, vcc, 0, v1, vcc
	global_load_dword v191, v[42:43], off
	v_add_co_u32_e32 v40, vcc, 0x30000, v0
	s_nop 1
	v_addc_co_u32_e32 v41, vcc, 0, v1, vcc
	global_load_dword v192, v[40:41], off
	v_add_co_u32_e32 v42, vcc, 0x36000, v0
	s_nop 1
	v_addc_co_u32_e32 v43, vcc, 0, v1, vcc
	global_load_dword v193, v[42:43], off
	v_add_co_u32_e32 v40, vcc, 0x3c000, v0
	s_nop 1
	v_addc_co_u32_e32 v41, vcc, 0, v1, vcc
	global_load_dword v194, v[40:41], off
	v_add_co_u32_e32 v42, vcc, 0x42000, v0
	s_nop 1
	v_addc_co_u32_e32 v43, vcc, 0, v1, vcc
	global_load_dword v195, v[42:43], off
	v_add_co_u32_e32 v40, vcc, 0x48000, v0
	s_nop 1
	v_addc_co_u32_e32 v41, vcc, 0, v1, vcc
	global_load_dword v196, v[40:41], off
	v_add_co_u32_e32 v42, vcc, 0x4e000, v0
	s_nop 1
	v_addc_co_u32_e32 v43, vcc, 0, v1, vcc
	global_load_dword v197, v[42:43], off
	v_add_co_u32_e32 v40, vcc, 0x54000, v0
	s_nop 1
	v_addc_co_u32_e32 v41, vcc, 0, v1, vcc
	global_load_dword v198, v[40:41], off
	v_add_co_u32_e32 v42, vcc, 0x5a000, v0
	s_nop 1
	v_addc_co_u32_e32 v43, vcc, 0, v1, vcc
	global_load_dword v199, v[42:43], off
	v_add_co_u32_e32 v40, vcc, 0x60000, v0
	s_nop 1
	v_addc_co_u32_e32 v41, vcc, 0, v1, vcc
	global_load_dword v200, v[40:41], off
	v_add_co_u32_e32 v42, vcc, 0x66000, v0
	s_nop 1
	v_addc_co_u32_e32 v43, vcc, 0, v1, vcc
	global_load_dword v201, v[42:43], off
	v_add_co_u32_e32 v40, vcc, 0x6c000, v0
	s_nop 1
	v_addc_co_u32_e32 v41, vcc, 0, v1, vcc
	global_load_dword v202, v[40:41], off
	v_add_co_u32_e32 v42, vcc, 0x72000, v0
	s_nop 1
	v_addc_co_u32_e32 v43, vcc, 0, v1, vcc
	global_load_dword v203, v[42:43], off
	v_add_co_u32_e32 v40, vcc, 0x78000, v0
	s_nop 1
	v_addc_co_u32_e32 v41, vcc, 0, v1, vcc
	global_load_dword v204, v[40:41], off
	v_add_co_u32_e32 v42, vcc, 0x7e000, v0
	s_nop 1
	v_addc_co_u32_e32 v43, vcc, 0, v1, vcc
	global_load_dword v205, v[42:43], off
	v_add_co_u32_e32 v40, vcc, 0x84000, v0
	s_nop 1
	v_addc_co_u32_e32 v41, vcc, 0, v1, vcc
	global_load_dword v206, v[40:41], off
	v_add_co_u32_e32 v42, vcc, 0x8a000, v0
	s_nop 1
	v_addc_co_u32_e32 v43, vcc, 0, v1, vcc
	global_load_dword v207, v[42:43], off
	v_add_co_u32_e32 v40, vcc, 0x90000, v0
	s_nop 1
	v_addc_co_u32_e32 v41, vcc, 0, v1, vcc
	global_load_dword v208, v[40:41], off
	v_add_co_u32_e32 v42, vcc, 0x96000, v0
	s_nop 1
	v_addc_co_u32_e32 v43, vcc, 0, v1, vcc
	global_load_dword v209, v[42:43], off
	v_add_co_u32_e32 v40, vcc, 0x9c000, v0
	s_nop 1
	v_addc_co_u32_e32 v41, vcc, 0, v1, vcc
	global_load_dword v210, v[40:41], off
	v_add_co_u32_e32 v42, vcc, 0xa2000, v0
	s_nop 1
	v_addc_co_u32_e32 v43, vcc, 0, v1, vcc
	global_load_dword v211, v[42:43], off
	v_add_co_u32_e32 v40, vcc, 0xa8000, v0
	s_nop 1
	v_addc_co_u32_e32 v41, vcc, 0, v1, vcc
	global_load_dword v212, v[40:41], off
	v_add_co_u32_e32 v42, vcc, 0xae000, v0
	s_nop 1
	v_addc_co_u32_e32 v43, vcc, 0, v1, vcc
	global_load_dword v213, v[42:43], off
	v_add_co_u32_e32 v40, vcc, 0xb4000, v0
	s_nop 1
	v_addc_co_u32_e32 v41, vcc, 0, v1, vcc
	global_load_dword v214, v[40:41], off
	v_add_co_u32_e32 v42, vcc, 0xba000, v0
	s_nop 1
	v_addc_co_u32_e32 v43, vcc, 0, v1, vcc
	global_load_dword v215, v[42:43], off
	v_add_co_u32_e32 v40, vcc, 0xc0000, v0
	s_nop 1
	v_addc_co_u32_e32 v41, vcc, 0, v1, vcc
	global_load_dword v216, v[40:41], off
	v_add_co_u32_e32 v42, vcc, 0xc6000, v0
	s_nop 1
	v_addc_co_u32_e32 v43, vcc, 0, v1, vcc
	global_load_dword v217, v[42:43], off
	v_add_co_u32_e32 v40, vcc, 0xcc000, v0
	s_nop 1
	v_addc_co_u32_e32 v41, vcc, 0, v1, vcc
	global_load_dword v218, v[40:41], off
	v_add_co_u32_e32 v42, vcc, 0xd2000, v0
	s_nop 1
	v_addc_co_u32_e32 v43, vcc, 0, v1, vcc
	global_load_dword v219, v[42:43], off
	v_add_co_u32_e32 v40, vcc, 0xd8000, v0
	s_nop 1
	v_addc_co_u32_e32 v41, vcc, 0, v1, vcc
	global_load_dword v220, v[40:41], off
	v_add_co_u32_e32 v42, vcc, 0xde000, v0
	s_nop 1
	v_addc_co_u32_e32 v43, vcc, 0, v1, vcc
	global_load_dword v221, v[42:43], off
	v_add_co_u32_e32 v40, vcc, 0xe4000, v0
	s_nop 1
	v_addc_co_u32_e32 v41, vcc, 0, v1, vcc
	global_load_dword v222, v[40:41], off
	v_add_co_u32_e32 v42, vcc, 0xea000, v0
	s_nop 1
	v_addc_co_u32_e32 v43, vcc, 0, v1, vcc
	global_load_dword v223, v[42:43], off
	v_add_co_u32_e32 v40, vcc, 0xf0000, v0
	s_nop 1
	v_addc_co_u32_e32 v41, vcc, 0, v1, vcc
	global_load_dword v224, v[40:41], off
	v_add_co_u32_e32 v42, vcc, 0xf6000, v0
	s_nop 1
	v_addc_co_u32_e32 v43, vcc, 0, v1, vcc
	global_load_dword v225, v[42:43], off
	v_add_co_u32_e32 v40, vcc, 0xfc000, v0
	s_nop 1
	v_addc_co_u32_e32 v41, vcc, 0, v1, vcc
	global_load_dword v226, v[40:41], off
	v_add_co_u32_e32 v42, vcc, 0x102000, v0
	s_nop 1
	v_addc_co_u32_e32 v43, vcc, 0, v1, vcc
	global_load_dword v227, v[42:43], off
	v_add_co_u32_e32 v40, vcc, 0x108000, v0
	s_nop 1
	v_addc_co_u32_e32 v41, vcc, 0, v1, vcc
; __device__ void phase_prep(const Params& p, int bid, int nb, char* lds) {
;     ...
;       for (int d = 0; d < 64; ++d) {
;         float wv = wp[(size_t)d * 6144];
;         const int dd = dq * 64 + d;
;         a0 += wv * sc[dd]; a1 += wv * sc[1024 + dd]; a2 += wv * sc[2048 + dd]; a3 += wv * sc[3072 + dd];
	global_load_dword v228, v[40:41], off
	v_add_co_u32_e32 v42, vcc, 0x10e000, v0
	s_nop 1
	v_addc_co_u32_e32 v43, vcc, 0, v1, vcc
	global_load_dword v229, v[42:43], off
	v_add_co_u32_e32 v40, vcc, 0x114000, v0
	s_nop 1
	v_addc_co_u32_e32 v41, vcc, 0, v1, vcc
	global_load_dword v230, v[40:41], off
	v_add_co_u32_e32 v42, vcc, 0x11a000, v0
	s_nop 1
	v_addc_co_u32_e32 v43, vcc, 0, v1, vcc
	global_load_dword v231, v[42:43], off
	v_add_co_u32_e32 v40, vcc, 0x120000, v0
	s_nop 1
	v_addc_co_u32_e32 v41, vcc, 0, v1, vcc
	global_load_dword v232, v[40:41], off
	v_add_co_u32_e32 v42, vcc, 0x126000, v0
	s_nop 1
	v_addc_co_u32_e32 v43, vcc, 0, v1, vcc
	global_load_dword v233, v[42:43], off
	v_add_co_u32_e32 v40, vcc, 0x12c000, v0
	s_nop 1
	v_addc_co_u32_e32 v41, vcc, 0, v1, vcc
	global_load_dword v234, v[40:41], off
	v_add_co_u32_e32 v42, vcc, 0x132000, v0
	s_nop 1
	v_addc_co_u32_e32 v43, vcc, 0, v1, vcc
	global_load_dword v235, v[42:43], off
	v_add_co_u32_e32 v40, vcc, 0x138000, v0
	s_nop 1
	v_addc_co_u32_e32 v41, vcc, 0, v1, vcc
	global_load_dword v236, v[40:41], off
	v_add_co_u32_e32 v42, vcc, 0x13e000, v0
	s_nop 1
	v_addc_co_u32_e32 v43, vcc, 0, v1, vcc
	global_load_dword v237, v[42:43], off
	v_add_co_u32_e32 v40, vcc, 0x144000, v0
	s_nop 1
	v_addc_co_u32_e32 v41, vcc, 0, v1, vcc
	global_load_dword v238, v[40:41], off
	v_add_co_u32_e32 v42, vcc, 0x14a000, v0
	s_nop 1
	v_addc_co_u32_e32 v43, vcc, 0, v1, vcc
	global_load_dword v239, v[42:43], off
	v_add_co_u32_e32 v40, vcc, 0x150000, v0
	s_nop 1
	v_addc_co_u32_e32 v41, vcc, 0, v1, vcc
	global_load_dword v240, v[40:41], off
	v_add_co_u32_e32 v42, vcc, 0x156000, v0
	s_nop 1
	v_addc_co_u32_e32 v43, vcc, 0, v1, vcc
	global_load_dword v241, v[42:43], off
	v_add_co_u32_e32 v40, vcc, 0x15c000, v0
	s_nop 1
	v_addc_co_u32_e32 v41, vcc, 0, v1, vcc
	global_load_dword v242, v[40:41], off
	v_add_co_u32_e32 v42, vcc, 0x162000, v0
	s_nop 1
	v_addc_co_u32_e32 v43, vcc, 0, v1, vcc
	global_load_dword v243, v[42:43], off
	v_add_co_u32_e32 v40, vcc, 0x168000, v0
	s_nop 1
	v_addc_co_u32_e32 v41, vcc, 0, v1, vcc
	global_load_dword v244, v[40:41], off
	v_add_co_u32_e32 v42, vcc, 0x16e000, v0
	s_nop 1
	v_addc_co_u32_e32 v43, vcc, 0, v1, vcc
	global_load_dword v245, v[42:43], off
	v_add_co_u32_e32 v40, vcc, 0x174000, v0
	s_nop 1
	v_addc_co_u32_e32 v41, vcc, 0, v1, vcc
	global_load_dword v246, v[40:41], off
	v_add_co_u32_e32 v42, vcc, 0x17a000, v0
	s_nop 1
	v_addc_co_u32_e32 v43, vcc, 0, v1, vcc
	global_load_dword v247, v[42:43], off
	ds_read_b128 v[40:43], v6
	ds_read_b128 v[56:59], v6 offset:16
	ds_read_b128 v[60:63], v6 offset:4096
	ds_read_b128 v[64:67], v6 offset:4112
	ds_read_b128 v[68:71], v6 offset:8192
	ds_read_b128 v[72:75], v6 offset:8208
	ds_read_b128 v[76:79], v6 offset:12288
	ds_read_b128 v[80:83], v6 offset:12304
	s_waitcnt lgkmcnt(7)
	v_mov_b32_e32 v92, v40
	s_waitcnt lgkmcnt(5)
	v_mov_b32_e32 v93, v60
	s_waitcnt lgkmcnt(3)
	v_mov_b32_e32 v95, v68
	s_waitcnt lgkmcnt(1)
	v_mov_b32_e32 v94, v76
	v_mov_b32_e32 v60, v41
	v_mov_b32_e32 v68, v77
	v_mov_b32_e32 v40, v42
	v_mov_b32_e32 v41, v62
	v_mov_b32_e32 v76, v78
	v_mov_b32_e32 v77, v70
	v_mov_b32_e32 v62, v43
	v_mov_b32_e32 v70, v79
	v_mov_b32_e32 v42, v56
	v_mov_b32_e32 v43, v64
	s_waitcnt lgkmcnt(0)
	v_mov_b32_e32 v78, v80
	v_mov_b32_e32 v79, v72
	v_mov_b32_e32 v64, v57
	v_mov_b32_e32 v72, v81
	v_mov_b32_e32 v56, v58
	v_mov_b32_e32 v57, v66
	v_mov_b32_e32 v80, v82
	v_mov_b32_e32 v81, v74
	v_mov_b32_e32 v66, v59
	v_mov_b32_e32 v74, v83
	v_add_u32_e32 v6, 32, v6
	s_waitcnt vmcnt(56)
	v_mov_b32_e32 v38, v184
	v_mov_b32_e32 v46, v185
	v_mov_b32_e32 v44, v186
	v_mov_b32_e32 v48, v187
	v_mov_b32_e32 v84, v188
	v_mov_b32_e32 v86, v189
	v_mov_b32_e32 v88, v190
	v_mov_b32_e32 v90, v191
	v_pk_fma_f32 v[2:3], v[38:39], v[92:93], v[2:3] op_sel_hi:[0,1,1]
	v_pk_fma_f32 v[4:5], v[38:39], v[94:95], v[4:5] op_sel_hi:[0,1,1]
	v_pk_fma_f32 v[2:3], v[46:47], v[60:61], v[2:3] op_sel_hi:[0,1,1]
	v_pk_fma_f32 v[4:5], v[46:47], v[68:69], v[4:5] op_sel_hi:[0,1,1]
	v_pk_fma_f32 v[2:3], v[44:45], v[40:41], v[2:3] op_sel_hi:[0,1,1]
	v_pk_fma_f32 v[4:5], v[44:45], v[76:77], v[4:5] op_sel_hi:[0,1,1]
	v_pk_fma_f32 v[2:3], v[48:49], v[62:63], v[2:3] op_sel_hi:[0,1,1]
	v_pk_fma_f32 v[4:5], v[48:49], v[70:71], v[4:5] op_sel_hi:[0,1,1]
	v_pk_fma_f32 v[2:3], v[84:85], v[42:43], v[2:3] op_sel_hi:[0,1,1]
	v_pk_fma_f32 v[4:5], v[84:85], v[78:79], v[4:5] op_sel_hi:[0,1,1]
	v_pk_fma_f32 v[2:3], v[86:87], v[64:65], v[2:3] op_sel_hi:[0,1,1]
	v_pk_fma_f32 v[4:5], v[86:87], v[72:73], v[4:5] op_sel_hi:[0,1,1]
	v_pk_fma_f32 v[2:3], v[88:89], v[56:57], v[2:3] op_sel_hi:[0,1,1]
	v_pk_fma_f32 v[4:5], v[88:89], v[80:81], v[4:5] op_sel_hi:[0,1,1]
	v_pk_fma_f32 v[2:3], v[90:91], v[66:67], v[2:3] op_sel_hi:[0,1,1]
	v_pk_fma_f32 v[4:5], v[90:91], v[74:75], v[4:5] op_sel_hi:[0,1,1]
	ds_read_b128 v[40:43], v6
	ds_read_b128 v[56:59], v6 offset:16
	ds_read_b128 v[60:63], v6 offset:4096
	ds_read_b128 v[64:67], v6 offset:4112
	ds_read_b128 v[68:71], v6 offset:8192
	ds_read_b128 v[72:75], v6 offset:8208
	ds_read_b128 v[76:79], v6 offset:12288
	ds_read_b128 v[80:83], v6 offset:12304
	s_waitcnt lgkmcnt(7)
	v_mov_b32_e32 v92, v40
	s_waitcnt lgkmcnt(5)
	v_mov_b32_e32 v93, v60
	s_waitcnt lgkmcnt(3)
	v_mov_b32_e32 v95, v68
	s_waitcnt lgkmcnt(1)
	v_mov_b32_e32 v94, v76
	v_mov_b32_e32 v60, v41
	v_mov_b32_e32 v68, v77
	v_mov_b32_e32 v40, v42
	v_mov_b32_e32 v41, v62
	v_mov_b32_e32 v76, v78
	v_mov_b32_e32 v77, v70
	v_mov_b32_e32 v62, v43
	v_mov_b32_e32 v70, v79
	v_mov_b32_e32 v42, v56
	v_mov_b32_e32 v43, v64
	s_waitcnt lgkmcnt(0)
; __device__ void phase_prep(const Params& p, int bid, int nb, char* lds) {
;     ...
;       for (int d = 0; d < 64; ++d) {
;         float wv = wp[(size_t)d * 6144];
;         const int dd = dq * 64 + d;
;         a0 += wv * sc[dd]; a1 += wv * sc[1024 + dd]; a2 += wv * sc[2048 + dd]; a3 += wv * sc[3072 + dd];
	v_mov_b32_e32 v78, v80
	v_mov_b32_e32 v79, v72
	v_mov_b32_e32 v64, v57
	v_mov_b32_e32 v72, v81
	v_mov_b32_e32 v56, v58
	v_mov_b32_e32 v57, v66
	v_mov_b32_e32 v80, v82
	v_mov_b32_e32 v81, v74
	v_mov_b32_e32 v66, v59
	v_mov_b32_e32 v74, v83
	v_add_u32_e32 v6, 32, v6
	s_waitcnt vmcnt(48)
	v_mov_b32_e32 v38, v192
	v_mov_b32_e32 v46, v193
	v_mov_b32_e32 v44, v194
	v_mov_b32_e32 v48, v195
	v_mov_b32_e32 v84, v196
	v_mov_b32_e32 v86, v197
	v_mov_b32_e32 v88, v198
	v_mov_b32_e32 v90, v199
	v_pk_fma_f32 v[2:3], v[38:39], v[92:93], v[2:3] op_sel_hi:[0,1,1]
	v_pk_fma_f32 v[4:5], v[38:39], v[94:95], v[4:5] op_sel_hi:[0,1,1]
	v_pk_fma_f32 v[2:3], v[46:47], v[60:61], v[2:3] op_sel_hi:[0,1,1]
	v_pk_fma_f32 v[4:5], v[46:47], v[68:69], v[4:5] op_sel_hi:[0,1,1]
	v_pk_fma_f32 v[2:3], v[44:45], v[40:41], v[2:3] op_sel_hi:[0,1,1]
	v_pk_fma_f32 v[4:5], v[44:45], v[76:77], v[4:5] op_sel_hi:[0,1,1]
	v_pk_fma_f32 v[2:3], v[48:49], v[62:63], v[2:3] op_sel_hi:[0,1,1]
	v_pk_fma_f32 v[4:5], v[48:49], v[70:71], v[4:5] op_sel_hi:[0,1,1]
	v_pk_fma_f32 v[2:3], v[84:85], v[42:43], v[2:3] op_sel_hi:[0,1,1]
	v_pk_fma_f32 v[4:5], v[84:85], v[78:79], v[4:5] op_sel_hi:[0,1,1]
	v_pk_fma_f32 v[2:3], v[86:87], v[64:65], v[2:3] op_sel_hi:[0,1,1]
	v_pk_fma_f32 v[4:5], v[86:87], v[72:73], v[4:5] op_sel_hi:[0,1,1]
	v_pk_fma_f32 v[2:3], v[88:89], v[56:57], v[2:3] op_sel_hi:[0,1,1]
	v_pk_fma_f32 v[4:5], v[88:89], v[80:81], v[4:5] op_sel_hi:[0,1,1]
	v_pk_fma_f32 v[2:3], v[90:91], v[66:67], v[2:3] op_sel_hi:[0,1,1]
	v_pk_fma_f32 v[4:5], v[90:91], v[74:75], v[4:5] op_sel_hi:[0,1,1]
	ds_read_b128 v[40:43], v6
	ds_read_b128 v[56:59], v6 offset:16
	ds_read_b128 v[60:63], v6 offset:4096
	ds_read_b128 v[64:67], v6 offset:4112
	ds_read_b128 v[68:71], v6 offset:8192
	ds_read_b128 v[72:75], v6 offset:8208
	ds_read_b128 v[76:79], v6 offset:12288
	ds_read_b128 v[80:83], v6 offset:12304
	s_waitcnt lgkmcnt(7)
	v_mov_b32_e32 v92, v40
	s_waitcnt lgkmcnt(5)
	v_mov_b32_e32 v93, v60
	s_waitcnt lgkmcnt(3)
	v_mov_b32_e32 v95, v68
	s_waitcnt lgkmcnt(1)
	v_mov_b32_e32 v94, v76
	v_mov_b32_e32 v60, v41
	v_mov_b32_e32 v68, v77
	v_mov_b32_e32 v40, v42
	v_mov_b32_e32 v41, v62
	v_mov_b32_e32 v76, v78
	v_mov_b32_e32 v77, v70
	v_mov_b32_e32 v62, v43
	v_mov_b32_e32 v70, v79
	v_mov_b32_e32 v42, v56
	v_mov_b32_e32 v43, v64
	s_waitcnt lgkmcnt(0)
	v_mov_b32_e32 v78, v80
	v_mov_b32_e32 v79, v72
	v_mov_b32_e32 v64, v57
	v_mov_b32_e32 v72, v81
	v_mov_b32_e32 v56, v58
	v_mov_b32_e32 v57, v66
	v_mov_b32_e32 v80, v82
	v_mov_b32_e32 v81, v74
	v_mov_b32_e32 v66, v59
	v_mov_b32_e32 v74, v83
	v_add_u32_e32 v6, 32, v6
	s_waitcnt vmcnt(40)
	v_mov_b32_e32 v38, v200
	v_mov_b32_e32 v46, v201
	v_mov_b32_e32 v44, v202
	v_mov_b32_e32 v48, v203
	v_mov_b32_e32 v84, v204
	v_mov_b32_e32 v86, v205
	v_mov_b32_e32 v88, v206
	v_mov_b32_e32 v90, v207
	v_pk_fma_f32 v[2:3], v[38:39], v[92:93], v[2:3] op_sel_hi:[0,1,1]
	v_pk_fma_f32 v[4:5], v[38:39], v[94:95], v[4:5] op_sel_hi:[0,1,1]
	v_pk_fma_f32 v[2:3], v[46:47], v[60:61], v[2:3] op_sel_hi:[0,1,1]
	v_pk_fma_f32 v[4:5], v[46:47], v[68:69], v[4:5] op_sel_hi:[0,1,1]
	v_pk_fma_f32 v[2:3], v[44:45], v[40:41], v[2:3] op_sel_hi:[0,1,1]
	v_pk_fma_f32 v[4:5], v[44:45], v[76:77], v[4:5] op_sel_hi:[0,1,1]
	v_pk_fma_f32 v[2:3], v[48:49], v[62:63], v[2:3] op_sel_hi:[0,1,1]
	v_pk_fma_f32 v[4:5], v[48:49], v[70:71], v[4:5] op_sel_hi:[0,1,1]
	v_pk_fma_f32 v[2:3], v[84:85], v[42:43], v[2:3] op_sel_hi:[0,1,1]
	v_pk_fma_f32 v[4:5], v[84:85], v[78:79], v[4:5] op_sel_hi:[0,1,1]
	v_pk_fma_f32 v[2:3], v[86:87], v[64:65], v[2:3] op_sel_hi:[0,1,1]
	v_pk_fma_f32 v[4:5], v[86:87], v[72:73], v[4:5] op_sel_hi:[0,1,1]
	v_pk_fma_f32 v[2:3], v[88:89], v[56:57], v[2:3] op_sel_hi:[0,1,1]
	v_pk_fma_f32 v[4:5], v[88:89], v[80:81], v[4:5] op_sel_hi:[0,1,1]
	v_pk_fma_f32 v[2:3], v[90:91], v[66:67], v[2:3] op_sel_hi:[0,1,1]
	v_pk_fma_f32 v[4:5], v[90:91], v[74:75], v[4:5] op_sel_hi:[0,1,1]
	ds_read_b128 v[40:43], v6
	ds_read_b128 v[56:59], v6 offset:16
	ds_read_b128 v[60:63], v6 offset:4096
	ds_read_b128 v[64:67], v6 offset:4112
	ds_read_b128 v[68:71], v6 offset:8192
	ds_read_b128 v[72:75], v6 offset:8208
	ds_read_b128 v[76:79], v6 offset:12288
	ds_read_b128 v[80:83], v6 offset:12304
	s_waitcnt lgkmcnt(7)
	v_mov_b32_e32 v92, v40
	s_waitcnt lgkmcnt(5)
	v_mov_b32_e32 v93, v60
	s_waitcnt lgkmcnt(3)
	v_mov_b32_e32 v95, v68
	s_waitcnt lgkmcnt(1)
	v_mov_b32_e32 v94, v76
	v_mov_b32_e32 v60, v41
	v_mov_b32_e32 v68, v77
	v_mov_b32_e32 v40, v42
	v_mov_b32_e32 v41, v62
	v_mov_b32_e32 v76, v78
	v_mov_b32_e32 v77, v70
	v_mov_b32_e32 v62, v43
	v_mov_b32_e32 v70, v79
	v_mov_b32_e32 v42, v56
	v_mov_b32_e32 v43, v64
	s_waitcnt lgkmcnt(0)
	v_mov_b32_e32 v78, v80
	v_mov_b32_e32 v79, v72
	v_mov_b32_e32 v64, v57
	v_mov_b32_e32 v72, v81
	v_mov_b32_e32 v56, v58
	v_mov_b32_e32 v57, v66
	v_mov_b32_e32 v80, v82
	v_mov_b32_e32 v81, v74
	v_mov_b32_e32 v66, v59
	v_mov_b32_e32 v74, v83
	v_add_u32_e32 v6, 32, v6
	s_waitcnt vmcnt(32)
; __device__ void phase_prep(const Params& p, int bid, int nb, char* lds) {
;     ...
;       for (int d = 0; d < 64; ++d) {
;         float wv = wp[(size_t)d * 6144];
;         const int dd = dq * 64 + d;
;         a0 += wv * sc[dd]; a1 += wv * sc[1024 + dd]; a2 += wv * sc[2048 + dd]; a3 += wv * sc[3072 + dd];
	v_mov_b32_e32 v38, v208
	v_mov_b32_e32 v46, v209
	v_mov_b32_e32 v44, v210
	v_mov_b32_e32 v48, v211
	v_mov_b32_e32 v84, v212
	v_mov_b32_e32 v86, v213
	v_mov_b32_e32 v88, v214
	v_mov_b32_e32 v90, v215
	v_pk_fma_f32 v[2:3], v[38:39], v[92:93], v[2:3] op_sel_hi:[0,1,1]
	v_pk_fma_f32 v[4:5], v[38:39], v[94:95], v[4:5] op_sel_hi:[0,1,1]
	v_pk_fma_f32 v[2:3], v[46:47], v[60:61], v[2:3] op_sel_hi:[0,1,1]
	v_pk_fma_f32 v[4:5], v[46:47], v[68:69], v[4:5] op_sel_hi:[0,1,1]
	v_pk_fma_f32 v[2:3], v[44:45], v[40:41], v[2:3] op_sel_hi:[0,1,1]
	v_pk_fma_f32 v[4:5], v[44:45], v[76:77], v[4:5] op_sel_hi:[0,1,1]
	v_pk_fma_f32 v[2:3], v[48:49], v[62:63], v[2:3] op_sel_hi:[0,1,1]
	v_pk_fma_f32 v[4:5], v[48:49], v[70:71], v[4:5] op_sel_hi:[0,1,1]
	v_pk_fma_f32 v[2:3], v[84:85], v[42:43], v[2:3] op_sel_hi:[0,1,1]
	v_pk_fma_f32 v[4:5], v[84:85], v[78:79], v[4:5] op_sel_hi:[0,1,1]
	v_pk_fma_f32 v[2:3], v[86:87], v[64:65], v[2:3] op_sel_hi:[0,1,1]
	v_pk_fma_f32 v[4:5], v[86:87], v[72:73], v[4:5] op_sel_hi:[0,1,1]
	v_pk_fma_f32 v[2:3], v[88:89], v[56:57], v[2:3] op_sel_hi:[0,1,1]
	v_pk_fma_f32 v[4:5], v[88:89], v[80:81], v[4:5] op_sel_hi:[0,1,1]
	v_pk_fma_f32 v[2:3], v[90:91], v[66:67], v[2:3] op_sel_hi:[0,1,1]
	v_pk_fma_f32 v[4:5], v[90:91], v[74:75], v[4:5] op_sel_hi:[0,1,1]
	ds_read_b128 v[40:43], v6
	ds_read_b128 v[56:59], v6 offset:16
	ds_read_b128 v[60:63], v6 offset:4096
	ds_read_b128 v[64:67], v6 offset:4112
	ds_read_b128 v[68:71], v6 offset:8192
	ds_read_b128 v[72:75], v6 offset:8208
	ds_read_b128 v[76:79], v6 offset:12288
	ds_read_b128 v[80:83], v6 offset:12304
	s_waitcnt lgkmcnt(7)
	v_mov_b32_e32 v92, v40
	s_waitcnt lgkmcnt(5)
	v_mov_b32_e32 v93, v60
	s_waitcnt lgkmcnt(3)
	v_mov_b32_e32 v95, v68
	s_waitcnt lgkmcnt(1)
	v_mov_b32_e32 v94, v76
	v_mov_b32_e32 v60, v41
	v_mov_b32_e32 v68, v77
	v_mov_b32_e32 v40, v42
	v_mov_b32_e32 v41, v62
	v_mov_b32_e32 v76, v78
	v_mov_b32_e32 v77, v70
	v_mov_b32_e32 v62, v43
	v_mov_b32_e32 v70, v79
	v_mov_b32_e32 v42, v56
	v_mov_b32_e32 v43, v64
	s_waitcnt lgkmcnt(0)
	v_mov_b32_e32 v78, v80
	v_mov_b32_e32 v79, v72
	v_mov_b32_e32 v64, v57
	v_mov_b32_e32 v72, v81
	v_mov_b32_e32 v56, v58
	v_mov_b32_e32 v57, v66
	v_mov_b32_e32 v80, v82
	v_mov_b32_e32 v81, v74
	v_mov_b32_e32 v66, v59
	v_mov_b32_e32 v74, v83
	v_add_u32_e32 v6, 32, v6
	s_waitcnt vmcnt(24)
	v_mov_b32_e32 v38, v216
	v_mov_b32_e32 v46, v217
	v_mov_b32_e32 v44, v218
	v_mov_b32_e32 v48, v219
	v_mov_b32_e32 v84, v220
	v_mov_b32_e32 v86, v221
	v_mov_b32_e32 v88, v222
	v_mov_b32_e32 v90, v223
	v_pk_fma_f32 v[2:3], v[38:39], v[92:93], v[2:3] op_sel_hi:[0,1,1]
	v_pk_fma_f32 v[4:5], v[38:39], v[94:95], v[4:5] op_sel_hi:[0,1,1]
	v_pk_fma_f32 v[2:3], v[46:47], v[60:61], v[2:3] op_sel_hi:[0,1,1]
	v_pk_fma_f32 v[4:5], v[46:47], v[68:69], v[4:5] op_sel_hi:[0,1,1]
	v_pk_fma_f32 v[2:3], v[44:45], v[40:41], v[2:3] op_sel_hi:[0,1,1]
	v_pk_fma_f32 v[4:5], v[44:45], v[76:77], v[4:5] op_sel_hi:[0,1,1]
	v_pk_fma_f32 v[2:3], v[48:49], v[62:63], v[2:3] op_sel_hi:[0,1,1]
	v_pk_fma_f32 v[4:5], v[48:49], v[70:71], v[4:5] op_sel_hi:[0,1,1]
	v_pk_fma_f32 v[2:3], v[84:85], v[42:43], v[2:3] op_sel_hi:[0,1,1]
	v_pk_fma_f32 v[4:5], v[84:85], v[78:79], v[4:5] op_sel_hi:[0,1,1]
	v_pk_fma_f32 v[2:3], v[86:87], v[64:65], v[2:3] op_sel_hi:[0,1,1]
	v_pk_fma_f32 v[4:5], v[86:87], v[72:73], v[4:5] op_sel_hi:[0,1,1]
	v_pk_fma_f32 v[2:3], v[88:89], v[56:57], v[2:3] op_sel_hi:[0,1,1]
	v_pk_fma_f32 v[4:5], v[88:89], v[80:81], v[4:5] op_sel_hi:[0,1,1]
	v_pk_fma_f32 v[2:3], v[90:91], v[66:67], v[2:3] op_sel_hi:[0,1,1]
	v_pk_fma_f32 v[4:5], v[90:91], v[74:75], v[4:5] op_sel_hi:[0,1,1]
	ds_read_b128 v[40:43], v6
	ds_read_b128 v[56:59], v6 offset:16
	ds_read_b128 v[60:63], v6 offset:4096
	ds_read_b128 v[64:67], v6 offset:4112
	ds_read_b128 v[68:71], v6 offset:8192
	ds_read_b128 v[72:75], v6 offset:8208
	ds_read_b128 v[76:79], v6 offset:12288
	ds_read_b128 v[80:83], v6 offset:12304
	s_waitcnt lgkmcnt(7)
	v_mov_b32_e32 v92, v40
	s_waitcnt lgkmcnt(5)
	v_mov_b32_e32 v93, v60
	s_waitcnt lgkmcnt(3)
	v_mov_b32_e32 v95, v68
	s_waitcnt lgkmcnt(1)
	v_mov_b32_e32 v94, v76
	v_mov_b32_e32 v60, v41
	v_mov_b32_e32 v68, v77
	v_mov_b32_e32 v40, v42
	v_mov_b32_e32 v41, v62
	v_mov_b32_e32 v76, v78
	v_mov_b32_e32 v77, v70
	v_mov_b32_e32 v62, v43
	v_mov_b32_e32 v70, v79
	v_mov_b32_e32 v42, v56
	v_mov_b32_e32 v43, v64
	s_waitcnt lgkmcnt(0)
	v_mov_b32_e32 v78, v80
	v_mov_b32_e32 v79, v72
	v_mov_b32_e32 v64, v57
	v_mov_b32_e32 v72, v81
	v_mov_b32_e32 v56, v58
	v_mov_b32_e32 v57, v66
	v_mov_b32_e32 v80, v82
	v_mov_b32_e32 v81, v74
	v_mov_b32_e32 v66, v59
	v_mov_b32_e32 v74, v83
	v_add_u32_e32 v6, 32, v6
	s_waitcnt vmcnt(16)
	v_mov_b32_e32 v38, v224
	v_mov_b32_e32 v46, v225
	v_mov_b32_e32 v44, v226
	v_mov_b32_e32 v48, v227
	v_mov_b32_e32 v84, v228
	v_mov_b32_e32 v86, v229
	v_mov_b32_e32 v88, v230
	v_mov_b32_e32 v90, v231
	v_pk_fma_f32 v[2:3], v[38:39], v[92:93], v[2:3] op_sel_hi:[0,1,1]
	v_pk_fma_f32 v[4:5], v[38:39], v[94:95], v[4:5] op_sel_hi:[0,1,1]
	v_pk_fma_f32 v[2:3], v[46:47], v[60:61], v[2:3] op_sel_hi:[0,1,1]
	v_pk_fma_f32 v[4:5], v[46:47], v[68:69], v[4:5] op_sel_hi:[0,1,1]
	v_pk_fma_f32 v[2:3], v[44:45], v[40:41], v[2:3] op_sel_hi:[0,1,1]
	v_pk_fma_f32 v[4:5], v[44:45], v[76:77], v[4:5] op_sel_hi:[0,1,1]
	v_pk_fma_f32 v[2:3], v[48:49], v[62:63], v[2:3] op_sel_hi:[0,1,1]
	v_pk_fma_f32 v[4:5], v[48:49], v[70:71], v[4:5] op_sel_hi:[0,1,1]
	v_pk_fma_f32 v[2:3], v[84:85], v[42:43], v[2:3] op_sel_hi:[0,1,1]
	v_pk_fma_f32 v[4:5], v[84:85], v[78:79], v[4:5] op_sel_hi:[0,1,1]
	v_pk_fma_f32 v[2:3], v[86:87], v[64:65], v[2:3] op_sel_hi:[0,1,1]
	v_pk_fma_f32 v[4:5], v[86:87], v[72:73], v[4:5] op_sel_hi:[0,1,1]
	v_pk_fma_f32 v[2:3], v[88:89], v[56:57], v[2:3] op_sel_hi:[0,1,1]
	v_pk_fma_f32 v[4:5], v[88:89], v[80:81], v[4:5] op_sel_hi:[0,1,1]
	v_pk_fma_f32 v[2:3], v[90:91], v[66:67], v[2:3] op_sel_hi:[0,1,1]
	v_pk_fma_f32 v[4:5], v[90:91], v[74:75], v[4:5] op_sel_hi:[0,1,1]
	ds_read_b128 v[40:43], v6
	ds_read_b128 v[56:59], v6 offset:16
	ds_read_b128 v[60:63], v6 offset:4096
	ds_read_b128 v[64:67], v6 offset:4112
	ds_read_b128 v[68:71], v6 offset:8192
	ds_read_b128 v[72:75], v6 offset:8208
	ds_read_b128 v[76:79], v6 offset:12288
	ds_read_b128 v[80:83], v6 offset:12304
	s_waitcnt lgkmcnt(7)
; __device__ void phase_prep(const Params& p, int bid, int nb, char* lds) {
;     ...
;       for (int d = 0; d < 64; ++d) {
;         float wv = wp[(size_t)d * 6144];
;         const int dd = dq * 64 + d;
;         a0 += wv * sc[dd]; a1 += wv * sc[1024 + dd]; a2 += wv * sc[2048 + dd]; a3 += wv * sc[3072 + dd];
;       }
;       red[(dq * 4 + 0) * 16 + cl] = a0; red[(dq * 4 + 1) * 16 + cl] = a1; red[(dq * 4 + 2) * 16 + cl] = a2; red[(dq * 4 + 3) * 16 + cl] = a3;
;       __syncthreads();
;       if (tid < 64) {
;         const int b = tid >> 4, cc = tid & 15;
;         float sum = 0.f;
; #pragma unroll
;         for (int q = 0; q < 16; ++q) sum += red[(q * 4 + b) * 16 + cc];
;         float* ada = (float*)(p.ws + OFF_ADA);
;         ada[b * 6144 + j * 16 + cc] = sum + p.b_ada[j * 16 + cc];
;       }
	v_mov_b32_e32 v92, v40
	s_waitcnt lgkmcnt(5)
	v_mov_b32_e32 v93, v60
	s_waitcnt lgkmcnt(3)
	v_mov_b32_e32 v95, v68
	s_waitcnt lgkmcnt(1)
	v_mov_b32_e32 v94, v76
	v_mov_b32_e32 v60, v41
	v_mov_b32_e32 v68, v77
	v_mov_b32_e32 v40, v42
	v_mov_b32_e32 v41, v62
	v_mov_b32_e32 v76, v78
	v_mov_b32_e32 v77, v70
	v_mov_b32_e32 v62, v43
	v_mov_b32_e32 v70, v79
	v_mov_b32_e32 v42, v56
	v_mov_b32_e32 v43, v64
	s_waitcnt lgkmcnt(0)
	v_mov_b32_e32 v78, v80
	v_mov_b32_e32 v79, v72
	v_mov_b32_e32 v64, v57
	v_mov_b32_e32 v72, v81
	v_mov_b32_e32 v56, v58
	v_mov_b32_e32 v57, v66
	v_mov_b32_e32 v80, v82
	v_mov_b32_e32 v81, v74
	v_mov_b32_e32 v66, v59
	v_mov_b32_e32 v74, v83
	v_add_u32_e32 v6, 32, v6
	s_waitcnt vmcnt(8)
	v_mov_b32_e32 v38, v232
	v_mov_b32_e32 v46, v233
	v_mov_b32_e32 v44, v234
	v_mov_b32_e32 v48, v235
	v_mov_b32_e32 v84, v236
	v_mov_b32_e32 v86, v237
	v_mov_b32_e32 v88, v238
	v_mov_b32_e32 v90, v239
	v_pk_fma_f32 v[2:3], v[38:39], v[92:93], v[2:3] op_sel_hi:[0,1,1]
	v_pk_fma_f32 v[4:5], v[38:39], v[94:95], v[4:5] op_sel_hi:[0,1,1]
	v_pk_fma_f32 v[2:3], v[46:47], v[60:61], v[2:3] op_sel_hi:[0,1,1]
	v_pk_fma_f32 v[4:5], v[46:47], v[68:69], v[4:5] op_sel_hi:[0,1,1]
	v_pk_fma_f32 v[2:3], v[44:45], v[40:41], v[2:3] op_sel_hi:[0,1,1]
	v_pk_fma_f32 v[4:5], v[44:45], v[76:77], v[4:5] op_sel_hi:[0,1,1]
	v_pk_fma_f32 v[2:3], v[48:49], v[62:63], v[2:3] op_sel_hi:[0,1,1]
	v_pk_fma_f32 v[4:5], v[48:49], v[70:71], v[4:5] op_sel_hi:[0,1,1]
	v_pk_fma_f32 v[2:3], v[84:85], v[42:43], v[2:3] op_sel_hi:[0,1,1]
	v_pk_fma_f32 v[4:5], v[84:85], v[78:79], v[4:5] op_sel_hi:[0,1,1]
	v_pk_fma_f32 v[2:3], v[86:87], v[64:65], v[2:3] op_sel_hi:[0,1,1]
	v_pk_fma_f32 v[4:5], v[86:87], v[72:73], v[4:5] op_sel_hi:[0,1,1]
	v_pk_fma_f32 v[2:3], v[88:89], v[56:57], v[2:3] op_sel_hi:[0,1,1]
	v_pk_fma_f32 v[4:5], v[88:89], v[80:81], v[4:5] op_sel_hi:[0,1,1]
	v_pk_fma_f32 v[2:3], v[90:91], v[66:67], v[2:3] op_sel_hi:[0,1,1]
	v_pk_fma_f32 v[4:5], v[90:91], v[74:75], v[4:5] op_sel_hi:[0,1,1]
	ds_read_b128 v[40:43], v6
	ds_read_b128 v[56:59], v6 offset:16
	ds_read_b128 v[60:63], v6 offset:4096
	ds_read_b128 v[64:67], v6 offset:4112
	ds_read_b128 v[68:71], v6 offset:8192
	ds_read_b128 v[72:75], v6 offset:8208
	ds_read_b128 v[76:79], v6 offset:12288
	ds_read_b128 v[80:83], v6 offset:12304
	s_waitcnt lgkmcnt(7)
	v_mov_b32_e32 v92, v40
	s_waitcnt lgkmcnt(5)
	v_mov_b32_e32 v93, v60
	s_waitcnt lgkmcnt(3)
	v_mov_b32_e32 v95, v68
	s_waitcnt lgkmcnt(1)
	v_mov_b32_e32 v94, v76
	v_mov_b32_e32 v60, v41
	v_mov_b32_e32 v68, v77
	v_mov_b32_e32 v40, v42
	v_mov_b32_e32 v41, v62
	v_mov_b32_e32 v76, v78
	v_mov_b32_e32 v77, v70
	v_mov_b32_e32 v62, v43
	v_mov_b32_e32 v70, v79
	v_mov_b32_e32 v42, v56
	v_mov_b32_e32 v43, v64
	s_waitcnt lgkmcnt(0)
	v_mov_b32_e32 v78, v80
	v_mov_b32_e32 v79, v72
	v_mov_b32_e32 v64, v57
	v_mov_b32_e32 v72, v81
	v_mov_b32_e32 v56, v58
	v_mov_b32_e32 v57, v66
	v_mov_b32_e32 v80, v82
	v_mov_b32_e32 v81, v74
	v_mov_b32_e32 v66, v59
	v_mov_b32_e32 v74, v83
	v_add_u32_e32 v6, 32, v6
	s_waitcnt vmcnt(0)
	v_mov_b32_e32 v38, v240
	v_mov_b32_e32 v46, v241
	v_mov_b32_e32 v44, v242
	v_mov_b32_e32 v48, v243
	v_mov_b32_e32 v84, v244
	v_mov_b32_e32 v86, v245
	v_mov_b32_e32 v88, v246
	v_mov_b32_e32 v90, v247
	v_pk_fma_f32 v[2:3], v[38:39], v[92:93], v[2:3] op_sel_hi:[0,1,1]
	v_pk_fma_f32 v[4:5], v[38:39], v[94:95], v[4:5] op_sel_hi:[0,1,1]
	v_pk_fma_f32 v[2:3], v[46:47], v[60:61], v[2:3] op_sel_hi:[0,1,1]
	v_pk_fma_f32 v[4:5], v[46:47], v[68:69], v[4:5] op_sel_hi:[0,1,1]
	v_pk_fma_f32 v[2:3], v[44:45], v[40:41], v[2:3] op_sel_hi:[0,1,1]
	v_pk_fma_f32 v[4:5], v[44:45], v[76:77], v[4:5] op_sel_hi:[0,1,1]
	v_pk_fma_f32 v[2:3], v[48:49], v[62:63], v[2:3] op_sel_hi:[0,1,1]
	v_pk_fma_f32 v[4:5], v[48:49], v[70:71], v[4:5] op_sel_hi:[0,1,1]
	v_pk_fma_f32 v[2:3], v[84:85], v[42:43], v[2:3] op_sel_hi:[0,1,1]
	v_pk_fma_f32 v[4:5], v[84:85], v[78:79], v[4:5] op_sel_hi:[0,1,1]
	v_pk_fma_f32 v[2:3], v[86:87], v[64:65], v[2:3] op_sel_hi:[0,1,1]
	v_pk_fma_f32 v[4:5], v[86:87], v[72:73], v[4:5] op_sel_hi:[0,1,1]
	v_pk_fma_f32 v[2:3], v[88:89], v[56:57], v[2:3] op_sel_hi:[0,1,1]
	v_pk_fma_f32 v[4:5], v[88:89], v[80:81], v[4:5] op_sel_hi:[0,1,1]
	v_pk_fma_f32 v[2:3], v[90:91], v[66:67], v[2:3] op_sel_hi:[0,1,1]
	v_pk_fma_f32 v[4:5], v[90:91], v[74:75], v[4:5] op_sel_hi:[0,1,1]
	v_add_u32_e32 v0, 0x4000, v51
	ds_write2_b32 v0, v2, v3 offset1:16
	ds_write2_b32 v0, v5, v4 offset0:32 offset1:48
	s_waitcnt lgkmcnt(0)
	s_barrier
	s_and_saveexec_b64 s[0:1], s[4:5]
	s_cbranch_execz .LBB0_22
	s_lshl_b32 s6, s46, 4
	v_or_b32_e32 v0, s6, v47
	v_ashrrev_i32_e32 v1, 31, v0
	v_lshl_add_u64 v[0:1], v[0:1], 2, s[78:79]
	global_load_dword v37, v[0:1], off
	ds_read2st64_b32 v[0:1], v52 offset0:64 offset1:65
	ds_read2st64_b32 v[2:3], v52 offset0:66 offset1:67
	ds_read2st64_b32 v[4:5], v52 offset0:68 offset1:69
	ds_read2st64_b32 v[6:7], v52 offset0:70 offset1:71
	ds_read2st64_b32 v[40:41], v52 offset0:72 offset1:73
	ds_read2st64_b32 v[42:43], v52 offset0:74 offset1:75
	ds_read2st64_b32 v[44:45], v52 offset0:76 offset1:77
	ds_read2st64_b32 v[48:49], v52 offset0:78 offset1:79
	s_waitcnt lgkmcnt(7)
	v_add_f32_e32 v0, 0, v0
	v_add_f32_e32 v0, v0, v1
	s_waitcnt lgkmcnt(6)
	v_add_f32_e32 v0, v0, v2
	v_add_f32_e32 v0, v0, v3
	s_waitcnt lgkmcnt(5)
	v_add_f32_e32 v0, v0, v4
	v_add_f32_e32 v0, v0, v5
	s_waitcnt lgkmcnt(4)
	v_add_f32_e32 v0, v0, v6
	v_add_f32_e32 v0, v0, v7
	s_waitcnt lgkmcnt(3)
	v_add_f32_e32 v0, v0, v40
	v_add_f32_e32 v0, v0, v41
	s_waitcnt lgkmcnt(2)
	v_add_f32_e32 v0, v0, v42
	v_add_f32_e32 v0, v0, v43
	s_waitcnt lgkmcnt(1)
	v_add_f32_e32 v0, v0, v44
	v_add_f32_e32 v0, v0, v45
	v_add_u32_e32 v56, s6, v53
	s_waitcnt lgkmcnt(0)
	v_add_f32_e32 v0, v0, v48
	v_ashrrev_i32_e32 v57, 31, v56
	v_add_f32_e32 v0, v0, v49
	s_waitcnt vmcnt(0)
	v_add_f32_e32 v2, v0, v37
	v_lshl_add_u64 v[0:1], v[56:57], 2, s[92:93]
	global_store_dword v[0:1], v2, off
	s_branch .LBB0_22
